# attention shift test on tiles after the first: per-lane maximum feeds the branch directly (no cross-half exchange); first tile and any positive run the full per-row test
# baseline (speedup 1.0000x reference)
.LBB0_885:
	s_nop 10
	s_cmp_lg_u64 s[64:65], 0
	s_cbranch_scc1 .Lhwat0_full
	v_max_f32_e32 v203, v80, v81
	v_max_f32_e32 v205, v64, v65
	v_max3_f32 v203, v203, v82, v83
	v_max3_f32 v205, v205, v66, v67
	v_max3_f32 v203, v203, v84, v85
	v_max3_f32 v205, v205, v68, v69
	v_max3_f32 v203, v203, v86, v87
	v_max3_f32 v205, v205, v70, v71
	v_max3_f32 v203, v203, v88, v89
	v_max3_f32 v205, v205, v72, v73
	v_max3_f32 v203, v203, v90, v91
	v_max3_f32 v205, v205, v74, v75
	v_max3_f32 v203, v203, v92, v93
	v_max3_f32 v205, v205, v76, v77
	v_max3_f32 v203, v203, v94, v95
	v_max3_f32 v205, v205, v78, v79
	v_max_f32_e32 v204, v203, v205
	v_cmp_lt_f32_e32 vcc, s83, v204
	s_cbranch_vccz .LBB0_887
.Lhwat0_full:
	v_max_f32_e32 v203, v80, v81
	v_max_f32_e32 v205, v64, v65
	v_max3_f32 v203, v203, v82, v83
	v_max3_f32 v205, v205, v66, v67
	v_max3_f32 v203, v203, v84, v85
	v_max3_f32 v205, v205, v68, v69
	v_max3_f32 v203, v203, v86, v87
	v_max3_f32 v205, v205, v70, v71
	v_max3_f32 v203, v203, v88, v89
	v_max3_f32 v205, v205, v72, v73
	v_max3_f32 v203, v203, v90, v91
	v_max3_f32 v205, v205, v74, v75
	v_max3_f32 v203, v203, v92, v93
	v_max3_f32 v205, v205, v76, v77
	v_max3_f32 v203, v203, v94, v95
	v_max3_f32 v205, v205, v78, v79
	s_nop 1
	v_permlane32_swap_b32_e32 v203, v205
	v_max_f32_e32 v204, v203, v205
	v_cmp_lt_f32_e32 vcc, s83, v204
	s_cmp_lg_u64 s[64:65], 0
	s_cbranch_scc1 .Lhwat0_firstchk
	s_cbranch_vccz .LBB0_887
	s_branch .Lhwat0_rare

.LBB0_2119:
	s_nop 10
	s_cmp_lg_u64 s[64:65], 0
	s_cbranch_scc1 .Lhwat1_full
	v_max_f32_e32 v203, v80, v81
	v_max_f32_e32 v205, v64, v65
	v_max3_f32 v203, v203, v82, v83
	v_max3_f32 v205, v205, v66, v67
	v_max3_f32 v203, v203, v84, v85
	v_max3_f32 v205, v205, v68, v69
	v_max3_f32 v203, v203, v86, v87
	v_max3_f32 v205, v205, v70, v71
	v_max3_f32 v203, v203, v88, v89
	v_max3_f32 v205, v205, v72, v73
	v_max3_f32 v203, v203, v90, v91
	v_max3_f32 v205, v205, v74, v75
	v_max3_f32 v203, v203, v92, v93
	v_max3_f32 v205, v205, v76, v77
	v_max3_f32 v203, v203, v94, v95
	v_max3_f32 v205, v205, v78, v79
	v_max_f32_e32 v204, v203, v205
	v_cmp_lt_f32_e32 vcc, s82, v204
	s_cbranch_vccz .LBB0_2121
.Lhwat1_full:
	v_max_f32_e32 v203, v80, v81
	v_max_f32_e32 v205, v64, v65
	v_max3_f32 v203, v203, v82, v83
	v_max3_f32 v205, v205, v66, v67
	v_max3_f32 v203, v203, v84, v85
	v_max3_f32 v205, v205, v68, v69
	v_max3_f32 v203, v203, v86, v87
	v_max3_f32 v205, v205, v70, v71
	v_max3_f32 v203, v203, v88, v89
	v_max3_f32 v205, v205, v72, v73
	v_max3_f32 v203, v203, v90, v91
	v_max3_f32 v205, v205, v74, v75
	v_max3_f32 v203, v203, v92, v93
	v_max3_f32 v205, v205, v76, v77
	v_max3_f32 v203, v203, v94, v95
	v_max3_f32 v205, v205, v78, v79
	s_nop 1
	v_permlane32_swap_b32_e32 v203, v205
	v_max_f32_e32 v204, v203, v205
	v_cmp_lt_f32_e32 vcc, s82, v204
	s_cmp_lg_u64 s[64:65], 0
	s_cbranch_scc1 .Lhwat1_firstchk
	s_cbranch_vccz .LBB0_2121
	s_branch .Lhwat1_rare
